# feat_b: sixth-round item of workgroups 208..239 (the ones with two transposed-store V^T items) moved to workgroups 48..79
# speedup vs baseline: 1.0045x; 1.0024x over previous
; DI void phase_feat_b(KP p, int l, char* lds) {
;     ...
;   for (int it = 2 * blockIdx.x + hbb; it < N1 + N2 + N3 + N4; it += 2 * gridDim.x) {
;     if (it < N1) {
.LBB0_218:
	v_readlane_b32 s2, v253, 8
	s_add_i32 s20, s20, s2
	v_readlane_b32 s2, v254, 52
	s_add_i32 s75, s75, s2
	s_sub_u32 s2, s20, 0xba0
	s_cmp_lt_u32 s2, 0x40
	s_cbranch_scc0 .Lfb_hi
	s_movk_i32 s20, 0x7fff
	s_branch .Lfb_done
.Lfb_hi:
	s_sub_u32 s2, s20, 0xc60
	s_cmp_lt_u32 s2, 0x40
	s_cbranch_scc0 .Lfb_done
	s_sub_i32 s20, s20, 0xc0
	s_sub_i32 s75, s75, 0x3000
